# v086 + RG-LRU conv v2: thread owns 3 consecutive rows of one channel group; six raw rows read/unpacked once feed all taps (LDS reads 22 -> 20, VALU 156 -> 108 per thread)
# baseline (speedup 1.0000x reference)
; #define LAS __attribute__((address_space(3)))
; DI u32x4 pack8f(const float (&f)[8]) { u32x4 r; r[0] = pk2(f[0], f[1]); r[1] = pk2(f[2], f[3]); r[2] = pk2(f[4], f[5]); r[3] = pk2(f[6], f[7]); return r; }
; DI void phase_rglru(const Params& p, unsigned char* shm) {
;     ...
; #pragma unroll
;             for (int j = 0; j < 3; ++j) {
;                 const int q = tid + 512 * j, cc = q % 24;
;                 float a8[8];
;                 { const f32x4 b0 = *(const LAS f32x4*)(cw + 768 + 8 * cc), b1 = *(const LAS f32x4*)(cw + 768 + 8 * cc + 4);
; #pragma unroll
;                   for (int e = 0; e < 4; ++e) { a8[e] = b0[e]; a8[4 + e] = b1[e]; } }
; #pragma unroll
;                 for (int jj = 0; jj < 4; ++jj) {
;                     float xin[8]; { const u32x4 xraw = *(const LAS u32x4*)(lds + XR + jj * TR + loff[j]); unpack8(xraw, xin); }
;                     const f32x4 w0 = *(const LAS f32x4*)(cw + jj * 192 + 8 * cc), w1 = *(const LAS f32x4*)(cw + jj * 192 + 8 * cc + 4);
; #pragma unroll
;                     for (int e = 0; e < 4; ++e) { a8[e] += w0[e] * xin[e]; a8[4 + e] += w1[e] * xin[4 + e]; }
;                 }
;                 *(LAS u32x4*)(lds + XC + loff[j]) = pack8f(a8);
;             }
.LBB0_845:
	s_waitcnt lgkmcnt(0)
	s_barrier
	v_mul_u32_u24_e32 v205, 0xaab, v192
	v_lshrrev_b32_e32 v205, 16, v205
	v_mul_u32_u24_e32 v170, 24, v205
	v_sub_u32_e32 v170, v192, v170
	v_min_u32_e32 v205, 20, v205
	v_mul_u32_u24_e32 v205, 0x4b0, v205
	v_lshl_add_u32 v205, v170, 4, v205
	v_lshlrev_b32_e32 v170, 5, v170
	v_add_u32_e32 v170, 0x1f900, v170
	ds_read_b128 v[210:213], v170
	ds_read_b128 v[214:217], v170 offset:16
	ds_read_b128 v[218:221], v170 offset:768
	ds_read_b128 v[222:225], v170 offset:784
	ds_read_b128 v[226:229], v170 offset:1536
	ds_read_b128 v[230:233], v170 offset:1552
	ds_read_b128 v[234:237], v170 offset:2304
	ds_read_b128 v[238:241], v170 offset:2320
	ds_read_b128 v[120:123], v170 offset:3072
	ds_read_b128 v[124:127], v170 offset:3088
	ds_read_b128 v[128:131], v170 offset:3072
	ds_read_b128 v[132:135], v170 offset:3088
	ds_read_b128 v[136:139], v170 offset:3072
	ds_read_b128 v[140:143], v170 offset:3088
	ds_read_b128 v[144:147], v205
	ds_read_b128 v[148:151], v205 offset:400
	s_waitcnt lgkmcnt(2)
	s_waitcnt lgkmcnt(1)
	v_lshlrev_b32_e32 v170, 16, v144
	v_and_b32_e32 v171, 0xffff0000, v144
	v_pk_fma_f32 v[120:121], v[210:211], v[170:171], v[120:121]
	v_lshlrev_b32_e32 v170, 16, v145
	v_and_b32_e32 v171, 0xffff0000, v145
	v_pk_fma_f32 v[122:123], v[212:213], v[170:171], v[122:123]
	v_lshlrev_b32_e32 v170, 16, v146
	v_and_b32_e32 v171, 0xffff0000, v146
	v_pk_fma_f32 v[124:125], v[214:215], v[170:171], v[124:125]
	v_lshlrev_b32_e32 v170, 16, v147
	v_and_b32_e32 v171, 0xffff0000, v147
	v_pk_fma_f32 v[126:127], v[216:217], v[170:171], v[126:127]
	ds_read_b128 v[144:147], v205 offset:800
	s_waitcnt lgkmcnt(1)
	v_lshlrev_b32_e32 v170, 16, v148
	v_and_b32_e32 v171, 0xffff0000, v148
	v_pk_fma_f32 v[120:121], v[218:219], v[170:171], v[120:121]
	v_pk_fma_f32 v[128:129], v[210:211], v[170:171], v[128:129]
	v_lshlrev_b32_e32 v170, 16, v149
	v_and_b32_e32 v171, 0xffff0000, v149
	v_pk_fma_f32 v[122:123], v[220:221], v[170:171], v[122:123]
	v_pk_fma_f32 v[130:131], v[212:213], v[170:171], v[130:131]
	v_lshlrev_b32_e32 v170, 16, v150
	v_and_b32_e32 v171, 0xffff0000, v150
	v_pk_fma_f32 v[124:125], v[222:223], v[170:171], v[124:125]
	v_pk_fma_f32 v[132:133], v[214:215], v[170:171], v[132:133]
	v_lshlrev_b32_e32 v170, 16, v151
	v_and_b32_e32 v171, 0xffff0000, v151
	v_pk_fma_f32 v[126:127], v[224:225], v[170:171], v[126:127]
	v_pk_fma_f32 v[134:135], v[216:217], v[170:171], v[134:135]
	ds_read_b128 v[148:151], v205 offset:1200
	s_waitcnt lgkmcnt(1)
	v_lshlrev_b32_e32 v170, 16, v144
	v_and_b32_e32 v171, 0xffff0000, v144
	v_pk_fma_f32 v[120:121], v[226:227], v[170:171], v[120:121]
	v_pk_fma_f32 v[128:129], v[218:219], v[170:171], v[128:129]
	v_pk_fma_f32 v[136:137], v[210:211], v[170:171], v[136:137]
	v_lshlrev_b32_e32 v170, 16, v145
	v_and_b32_e32 v171, 0xffff0000, v145
	v_pk_fma_f32 v[122:123], v[228:229], v[170:171], v[122:123]
	v_pk_fma_f32 v[130:131], v[220:221], v[170:171], v[130:131]
	v_pk_fma_f32 v[138:139], v[212:213], v[170:171], v[138:139]
	v_lshlrev_b32_e32 v170, 16, v146
	v_and_b32_e32 v171, 0xffff0000, v146
	v_pk_fma_f32 v[124:125], v[230:231], v[170:171], v[124:125]
	v_pk_fma_f32 v[132:133], v[222:223], v[170:171], v[132:133]
	v_pk_fma_f32 v[140:141], v[214:215], v[170:171], v[140:141]
	v_lshlrev_b32_e32 v170, 16, v147
	v_and_b32_e32 v171, 0xffff0000, v147
	v_pk_fma_f32 v[126:127], v[232:233], v[170:171], v[126:127]
	v_pk_fma_f32 v[134:135], v[224:225], v[170:171], v[134:135]
	v_pk_fma_f32 v[142:143], v[216:217], v[170:171], v[142:143]
	ds_read_b128 v[144:147], v205 offset:1600
	s_waitcnt lgkmcnt(1)
	v_lshlrev_b32_e32 v170, 16, v148
	v_and_b32_e32 v171, 0xffff0000, v148
	v_pk_fma_f32 v[120:121], v[234:235], v[170:171], v[120:121]
	v_pk_fma_f32 v[128:129], v[226:227], v[170:171], v[128:129]
	v_pk_fma_f32 v[136:137], v[218:219], v[170:171], v[136:137]
	v_lshlrev_b32_e32 v170, 16, v149
	v_and_b32_e32 v171, 0xffff0000, v149
	v_pk_fma_f32 v[122:123], v[236:237], v[170:171], v[122:123]
	v_pk_fma_f32 v[130:131], v[228:229], v[170:171], v[130:131]
	v_pk_fma_f32 v[138:139], v[220:221], v[170:171], v[138:139]
	v_lshlrev_b32_e32 v170, 16, v150
	v_and_b32_e32 v171, 0xffff0000, v150
	v_pk_fma_f32 v[124:125], v[238:239], v[170:171], v[124:125]
	v_pk_fma_f32 v[132:133], v[230:231], v[170:171], v[132:133]
	v_pk_fma_f32 v[140:141], v[222:223], v[170:171], v[140:141]
	v_lshlrev_b32_e32 v170, 16, v151
	v_and_b32_e32 v171, 0xffff0000, v151
	v_pk_fma_f32 v[126:127], v[240:241], v[170:171], v[126:127]
	v_pk_fma_f32 v[134:135], v[232:233], v[170:171], v[134:135]
	v_pk_fma_f32 v[142:143], v[224:225], v[170:171], v[142:143]
	ds_read_b128 v[148:151], v205 offset:2000
	v_cvt_pk_bf16_f32 v120, v120, v121
	v_cvt_pk_bf16_f32 v121, v122, v123
	v_cvt_pk_bf16_f32 v122, v124, v125
	v_cvt_pk_bf16_f32 v123, v126, v127
	ds_write_b128 v205, v[120:123] offset:26880
	s_waitcnt lgkmcnt(2)
	v_lshlrev_b32_e32 v170, 16, v144
	v_and_b32_e32 v171, 0xffff0000, v144
	v_pk_fma_f32 v[128:129], v[234:235], v[170:171], v[128:129]
	v_pk_fma_f32 v[136:137], v[226:227], v[170:171], v[136:137]
	v_lshlrev_b32_e32 v170, 16, v145
	v_and_b32_e32 v171, 0xffff0000, v145
	v_pk_fma_f32 v[130:131], v[236:237], v[170:171], v[130:131]
	v_pk_fma_f32 v[138:139], v[228:229], v[170:171], v[138:139]
	v_lshlrev_b32_e32 v170, 16, v146
	v_and_b32_e32 v171, 0xffff0000, v146
	v_pk_fma_f32 v[132:133], v[238:239], v[170:171], v[132:133]
	v_pk_fma_f32 v[140:141], v[230:231], v[170:171], v[140:141]
	v_lshlrev_b32_e32 v170, 16, v147
	v_and_b32_e32 v171, 0xffff0000, v147
	v_pk_fma_f32 v[134:135], v[240:241], v[170:171], v[134:135]
	v_pk_fma_f32 v[142:143], v[232:233], v[170:171], v[142:143]
	v_cvt_pk_bf16_f32 v128, v128, v129
	v_cvt_pk_bf16_f32 v129, v130, v131
	v_cvt_pk_bf16_f32 v130, v132, v133
	v_cvt_pk_bf16_f32 v131, v134, v135
	ds_write_b128 v205, v[128:131] offset:27280
	s_waitcnt lgkmcnt(2)
	v_lshlrev_b32_e32 v170, 16, v148
	v_and_b32_e32 v171, 0xffff0000, v148
	v_pk_fma_f32 v[136:137], v[234:235], v[170:171], v[136:137]
	v_lshlrev_b32_e32 v170, 16, v149
	v_and_b32_e32 v171, 0xffff0000, v149
	v_pk_fma_f32 v[138:139], v[236:237], v[170:171], v[138:139]
	v_lshlrev_b32_e32 v170, 16, v150
	v_and_b32_e32 v171, 0xffff0000, v150
	v_pk_fma_f32 v[140:141], v[238:239], v[170:171], v[140:141]
	v_lshlrev_b32_e32 v170, 16, v151
	v_and_b32_e32 v171, 0xffff0000, v151
	v_pk_fma_f32 v[142:143], v[240:241], v[170:171], v[142:143]
	v_cvt_pk_bf16_f32 v136, v136, v137
	v_cvt_pk_bf16_f32 v137, v138, v139
	v_cvt_pk_bf16_f32 v138, v140, v141
	v_cvt_pk_bf16_f32 v139, v142, v143
	ds_write_b128 v205, v[136:139] offset:27680
	v_cmp_gt_u32_e32 vcc, 24, v192
	s_and_saveexec_b64 s[2:3], vcc
	s_cbranch_execz .Lconv_x_done
; #define LAS __attribute__((address_space(3)))
; DI u32x4 pack8f(const float (&f)[8]) { u32x4 r; r[0] = pk2(f[0], f[1]); r[1] = pk2(f[2], f[3]); r[2] = pk2(f[4], f[5]); r[3] = pk2(f[6], f[7]); return r; }
; DI void phase_rglru(const Params& p, unsigned char* shm) {
;     ...
; #pragma unroll
;             for (int j = 0; j < 3; ++j) {
;                 const int q = tid + 512 * j, cc = q % 24;
;                 float a8[8];
;                 { const f32x4 b0 = *(const LAS f32x4*)(cw + 768 + 8 * cc), b1 = *(const LAS f32x4*)(cw + 768 + 8 * cc + 4);
; #pragma unroll
;                   for (int e = 0; e < 4; ++e) { a8[e] = b0[e]; a8[4 + e] = b1[e]; } }
; #pragma unroll
;                 for (int jj = 0; jj < 4; ++jj) {
;                     float xin[8]; { const u32x4 xraw = *(const LAS u32x4*)(lds + XR + jj * TR + loff[j]); unpack8(xraw, xin); }
;                     const f32x4 w0 = *(const LAS f32x4*)(cw + jj * 192 + 8 * cc), w1 = *(const LAS f32x4*)(cw + jj * 192 + 8 * cc + 4);
; #pragma unroll
;                     for (int e = 0; e < 4; ++e) { a8[e] += w0[e] * xin[e]; a8[4 + e] += w1[e] * xin[4 + e]; }
;                 }
;                 *(LAS u32x4*)(lds + XC + loff[j]) = pack8f(a8);
;             }
	v_lshlrev_b32_e32 v171, 1, v205
	v_add_u32_e32 v171, 0x1f900, v171
	ds_read_b128 v[120:123], v171 offset:3072
	ds_read_b128 v[124:127], v171 offset:3088
	ds_read_b128 v[128:131], v205 offset:25200
	ds_read_b128 v[132:135], v205 offset:25600
	ds_read_b128 v[136:139], v205 offset:26000
	ds_read_b128 v[140:143], v205 offset:26400
	s_waitcnt lgkmcnt(4)
	s_waitcnt lgkmcnt(3)
	v_lshlrev_b32_e32 v170, 16, v128
	v_and_b32_e32 v171, 0xffff0000, v128
	v_pk_fma_f32 v[120:121], v[210:211], v[170:171], v[120:121]
	v_lshlrev_b32_e32 v170, 16, v129
	v_and_b32_e32 v171, 0xffff0000, v129
	v_pk_fma_f32 v[122:123], v[212:213], v[170:171], v[122:123]
	v_lshlrev_b32_e32 v170, 16, v130
	v_and_b32_e32 v171, 0xffff0000, v130
	v_pk_fma_f32 v[124:125], v[214:215], v[170:171], v[124:125]
	v_lshlrev_b32_e32 v170, 16, v131
	v_and_b32_e32 v171, 0xffff0000, v131
	v_pk_fma_f32 v[126:127], v[216:217], v[170:171], v[126:127]
	s_waitcnt lgkmcnt(2)
	v_lshlrev_b32_e32 v170, 16, v132
	v_and_b32_e32 v171, 0xffff0000, v132
	v_pk_fma_f32 v[120:121], v[218:219], v[170:171], v[120:121]
	v_lshlrev_b32_e32 v170, 16, v133
	v_and_b32_e32 v171, 0xffff0000, v133
	v_pk_fma_f32 v[122:123], v[220:221], v[170:171], v[122:123]
	v_lshlrev_b32_e32 v170, 16, v134
	v_and_b32_e32 v171, 0xffff0000, v134
	v_pk_fma_f32 v[124:125], v[222:223], v[170:171], v[124:125]
	v_lshlrev_b32_e32 v170, 16, v135
	v_and_b32_e32 v171, 0xffff0000, v135
	v_pk_fma_f32 v[126:127], v[224:225], v[170:171], v[126:127]
	s_waitcnt lgkmcnt(1)
	v_lshlrev_b32_e32 v170, 16, v136
	v_and_b32_e32 v171, 0xffff0000, v136
	v_pk_fma_f32 v[120:121], v[226:227], v[170:171], v[120:121]
	v_lshlrev_b32_e32 v170, 16, v137
	v_and_b32_e32 v171, 0xffff0000, v137
	v_pk_fma_f32 v[122:123], v[228:229], v[170:171], v[122:123]
	v_lshlrev_b32_e32 v170, 16, v138
	v_and_b32_e32 v171, 0xffff0000, v138
	v_pk_fma_f32 v[124:125], v[230:231], v[170:171], v[124:125]
	v_lshlrev_b32_e32 v170, 16, v139
	v_and_b32_e32 v171, 0xffff0000, v139
	v_pk_fma_f32 v[126:127], v[232:233], v[170:171], v[126:127]
	s_waitcnt lgkmcnt(0)
	v_lshlrev_b32_e32 v170, 16, v140
	v_and_b32_e32 v171, 0xffff0000, v140
	v_pk_fma_f32 v[120:121], v[234:235], v[170:171], v[120:121]
	v_lshlrev_b32_e32 v170, 16, v141
	v_and_b32_e32 v171, 0xffff0000, v141
	v_pk_fma_f32 v[122:123], v[236:237], v[170:171], v[122:123]
	v_lshlrev_b32_e32 v170, 16, v142
	v_and_b32_e32 v171, 0xffff0000, v142
	v_pk_fma_f32 v[124:125], v[238:239], v[170:171], v[124:125]
	v_lshlrev_b32_e32 v170, 16, v143
	v_and_b32_e32 v171, 0xffff0000, v143
	v_pk_fma_f32 v[126:127], v[240:241], v[170:171], v[126:127]
	v_cvt_pk_bf16_f32 v120, v120, v121
	v_cvt_pk_bf16_f32 v121, v122, v123
	v_cvt_pk_bf16_f32 v122, v124, v125
	v_cvt_pk_bf16_f32 v123, v126, v127
	ds_write_b128 v205, v[120:123] offset:52080
